# v118 + per-phase s_setprio in the own-phase attention loop
# speedup vs baseline: 1.0039x; 1.0039x over previous
.LBB0_929:
	s_setprio 1
	v_add_u32_e32 v73, 0, v120
	v_add_u32_e32 v78, 0x10000, v73
	v_cvt_pk_bf16_f32 v74, v127, v124
	v_cvt_pk_bf16_f32 v75, v125, v126
	v_cvt_pk_bf16_f32 v76, v121, v122
	v_cvt_pk_bf16_f32 v77, v123, v70
	v_cvt_pk_bf16_f32 v160, v71, v72
	v_cvt_pk_bf16_f32 v161, v64, v65
	v_cvt_pk_bf16_f32 v162, v66, v67
	v_cvt_pk_bf16_f32 v163, v68, v69
	v_add_u32_e32 v79, 0x10800, v73
	ds_read_b64_tr_b16 v[164:165], v78
	ds_read_b64_tr_b16 v[166:167], v79
	s_waitcnt lgkmcnt(0)
	v_mfma_f32_32x32x16_bf16 v[48:63], v[164:167], v[74:77], v[48:63]
	v_add_u32_e32 v78, 0x11000, v73
	v_add_u32_e32 v79, 0x11800, v73
	ds_read_b64_tr_b16 v[170:171], v79
	ds_read_b64_tr_b16 v[168:169], v78
	v_add_u32_e32 v78, 0x10100, v73
	v_add_u32_e32 v79, 0x10900, v73
	ds_read_b64_tr_b16 v[164:165], v78
	ds_read_b64_tr_b16 v[166:167], v79
	v_add_u32_e32 v78, 0x11100, v73
	v_add_u32_e32 v79, 0x11900, v73
	s_waitcnt lgkmcnt(2)
	v_mfma_f32_32x32x16_bf16 v[48:63], v[168:171], v[160:163], v[48:63]
	ds_read_b64_tr_b16 v[168:169], v78
	ds_read_b64_tr_b16 v[170:171], v79
	v_add_u32_e32 v79, 0x10200, v73
	v_add_f32_e32 v78, 0, v127
	v_add_u32_e32 v127, 0x10a00, v73
	v_add_f32_e32 v78, v124, v78
	v_add_f32_e32 v78, v125, v78
	v_add_f32_e32 v78, v126, v78
	s_waitcnt lgkmcnt(2)
	v_mfma_f32_32x32x16_bf16 v[32:47], v[164:167], v[74:77], v[32:47]
	ds_read_b64_tr_b16 v[164:165], v79
	ds_read_b64_tr_b16 v[166:167], v127
	v_add_u32_e32 v79, 0x11200, v73
	v_add_u32_e32 v126, 0x11a00, v73
	ds_read_b64_tr_b16 v[124:125], v79
	ds_read_b64_tr_b16 v[126:127], v126
	v_add_u32_e32 v79, 0x10300, v73
	v_add_f32_e32 v78, v121, v78
	v_add_u32_e32 v121, 0x10b00, v73
	s_waitcnt lgkmcnt(2)
	v_mfma_f32_32x32x16_bf16 v[16:31], v[164:167], v[74:77], v[16:31]
	ds_read_b64_tr_b16 v[164:165], v79
	ds_read_b64_tr_b16 v[166:167], v121
	v_add_f32_e32 v78, v122, v78
	v_add_f32_e32 v78, v123, v78
	v_add_f32_e32 v70, v70, v78
	v_add_f32_e32 v70, v71, v70
	v_add_f32_e32 v78, v72, v70
	v_add_u32_e32 v70, 0x11300, v73
	s_waitcnt lgkmcnt(0)
	v_mfma_f32_32x32x16_bf16 v[0:15], v[164:167], v[74:77], v[0:15]
	v_add_u32_e32 v72, 0x11b00, v73
	ds_read_b64_tr_b16 v[70:71], v70
	ds_read_b64_tr_b16 v[72:73], v72
	v_add_f32_e32 v64, v64, v78
	v_add_f32_e32 v64, v65, v64
	v_add_f32_e32 v64, v66, v64
	v_add_f32_e32 v64, v67, v64
	v_add_f32_e32 v64, v68, v64
	v_mfma_f32_32x32x16_bf16 v[32:47], v[168:171], v[160:163], v[32:47]
	v_add_f32_e32 v64, v69, v64
	s_add_i32 s38, s38, 1
	v_add_f32_e32 v159, v159, v64
	v_add_u32_e32 v120, 0x2000, v120
	v_add_u32_e32 v119, 0x2000, v119
	v_add_u32_e32 v118, 0x2000, v118
	v_add_u32_e32 v117, 0x2000, v117
	v_mfma_f32_32x32x16_bf16 v[16:31], v[124:127], v[160:163], v[16:31]
	v_add_u32_e32 v116, 0x2000, v116
	v_add_u32_e32 v115, 0x2000, v115
	v_add_u32_e32 v114, 0x2000, v114
	v_add_u32_e32 v113, 0x2000, v113
	s_cmp_lg_u32 s38, 1
	v_add_u32_e32 v112, 0x2000, v112
	s_waitcnt lgkmcnt(0)
	v_mfma_f32_32x32x16_bf16 v[0:15], v[70:73], v[160:163], v[0:15]
	s_cbranch_scc0 .LBB0_932
.LBB0_930:
	s_setprio 1
	v_add_u32_e32 v64, 0, v112
	ds_read_b128 v[64:67], v64
	v_add_u32_e32 v68, 0, v113
	ds_read_b128 v[122:125], v68
	v_add_u32_e32 v121, 0, v114
	s_cmp_lg_u32 s38, 0
	s_waitcnt lgkmcnt(1)
	v_mfma_f32_32x32x16_bf16 v[64:79], v[64:67], v[80:83], 0
	s_waitcnt lgkmcnt(0)
	v_mfma_f32_32x32x16_bf16 v[64:79], v[122:125], v[84:87], v[64:79]
	ds_read_b128 v[122:125], v121
	v_add_u32_e32 v121, 0, v115
	ds_read_b128 v[160:163], v121
	v_add_u32_e32 v121, 0, v116
	s_waitcnt lgkmcnt(1)
	v_mfma_f32_32x32x16_bf16 v[64:79], v[122:125], v[88:91], v[64:79]
	ds_read_b128 v[122:125], v121
	v_add_u32_e32 v121, 0, v117
	s_waitcnt lgkmcnt(1)
	v_mfma_f32_32x32x16_bf16 v[64:79], v[160:163], v[92:95], v[64:79]
	ds_read_b128 v[160:163], v121
	v_add_u32_e32 v121, 0, v118
	s_waitcnt lgkmcnt(1)
	v_mfma_f32_32x32x16_bf16 v[64:79], v[122:125], v[96:99], v[64:79]
	ds_read_b128 v[122:125], v121
	v_add_u32_e32 v121, 0, v119
	s_waitcnt lgkmcnt(1)
	v_mfma_f32_32x32x16_bf16 v[64:79], v[160:163], v[100:103], v[64:79]
	ds_read_b128 v[160:163], v121
	s_waitcnt lgkmcnt(1)
	v_mfma_f32_32x32x16_bf16 v[64:79], v[122:125], v[104:107], v[64:79]
	s_waitcnt lgkmcnt(0)
	v_mfma_f32_32x32x16_bf16 v[64:79], v[160:163], v[108:111], v[64:79]
	s_setprio 0
	s_nop 11
	v_exp_f32_e32 v127, v64
	v_exp_f32_e32 v124, v65
	v_exp_f32_e32 v125, v66
	v_exp_f32_e32 v126, v67
	v_exp_f32_e32 v121, v68
	v_exp_f32_e32 v122, v69
	v_exp_f32_e32 v123, v70
	v_exp_f32_e32 v70, v71
	v_exp_f32_e32 v71, v72
	v_exp_f32_e32 v72, v73
	v_exp_f32_e32 v64, v74
	v_exp_f32_e32 v65, v75
	v_exp_f32_e32 v66, v76
	v_exp_f32_e32 v67, v77
	v_exp_f32_e32 v68, v78
	v_exp_f32_e32 v69, v79
	s_cbranch_scc1 .LBB0_929
	v_cndmask_b32_e64 v127, v127, 0, s[4:5]
	v_cndmask_b32_e64 v124, 0, v124, s[6:7]
	v_cndmask_b32_e64 v125, v125, 0, s[8:9]
	v_cndmask_b32_e64 v126, v126, 0, s[10:11]
	v_cndmask_b32_e64 v121, v121, 0, s[12:13]
	v_cndmask_b32_e64 v122, v122, 0, s[14:15]
	v_cndmask_b32_e64 v123, v123, 0, s[16:17]
	v_cndmask_b32_e64 v70, v70, 0, s[18:19]
	v_cndmask_b32_e64 v71, v71, 0, s[20:21]
	v_cndmask_b32_e64 v72, v72, 0, s[22:23]
	v_cndmask_b32_e64 v64, v64, 0, s[24:25]
	v_cndmask_b32_e64 v65, v65, 0, s[26:27]
	v_cndmask_b32_e64 v66, v66, 0, s[28:29]
	v_cndmask_b32_e64 v67, v67, 0, s[30:31]
	v_cndmask_b32_e64 v68, v68, 0, s[34:35]
	v_cndmask_b32_e64 v69, v69, 0, s[36:37]
	s_branch .LBB0_929
.LBB0_932:
	s_waitcnt vmcnt(0)
	s_setprio 0
	v_add_u32_e32 v64, s96, v133
	v_lshl_add_u32 v144, v64, 1, v64
	v_add_u32_e32 v138, 1, v144
	v_lshlrev_b64 v[64:65], 8, v[138:139]
	v_add_u32_e32 v138, 49, v144
	v_lshl_add_u64 v[64:65], v[140:141], 0, v[64:65]
	v_lshlrev_b64 v[66:67], 8, v[138:139]
	v_add_u32_e32 v138, 2, v144
	v_lshl_add_u64 v[66:67], v[140:141], 0, v[66:67]
	v_mov_b64_e32 v[120:121], v[206:207]
	v_mov_b64_e32 v[122:123], v[208:209]
	v_mov_b64_e32 v[112:113], v[210:211]
	v_mov_b64_e32 v[114:115], v[212:213]
	v_mov_b64_e32 v[124:125], v[222:223]
	v_mov_b64_e32 v[126:127], v[224:225]
	v_mov_b64_e32 v[116:117], v[226:227]
	v_mov_b64_e32 v[118:119], v[228:229]
	v_mov_b64_e32 v[104:105], v[214:215]
	v_mov_b64_e32 v[106:107], v[216:217]
	v_mov_b64_e32 v[96:97], v[218:219]
	v_mov_b64_e32 v[98:99], v[220:221]
	v_mov_b64_e32 v[108:109], v[230:231]
	v_mov_b64_e32 v[110:111], v[232:233]
	v_mov_b64_e32 v[100:101], v[234:235]
	v_mov_b64_e32 v[102:103], v[236:237]
	v_lshlrev_b64 v[64:65], 8, v[138:139]
	v_add_u32_e32 v138, 50, v144
	v_lshlrev_b64 v[66:67], 8, v[138:139]
	v_lshl_add_u64 v[64:65], v[140:141], 0, v[64:65]
	v_lshl_add_u64 v[68:69], v[140:141], 0, v[66:67]
	v_mov_b64_e32 v[88:89], v[238:239]
	v_mov_b64_e32 v[90:91], v[240:241]
	v_mov_b64_e32 v[80:81], v[242:243]
	v_mov_b64_e32 v[82:83], v[244:245]
	global_load_dwordx4 v[92:95], v[68:69], off
	global_load_dwordx4 v[84:87], v[68:69], off offset:64
	v_mov_b64_e32 v[72:73], v[246:247]
	v_mov_b64_e32 v[74:75], v[248:249]
	s_nop 0
	global_load_dwordx4 v[64:67], v[64:65], off offset:192
	s_nop 0
	global_load_dwordx4 v[76:79], v[68:69], off offset:128
	s_nop 0
	global_load_dwordx4 v[68:71], v[68:69], off offset:192
	ds_bpermute_b32 v161, v137, v159
	s_cmp_eq_u32 s97, 0
	s_cselect_b64 s[86:87], -1, 0
	s_and_b64 vcc, exec, s[86:87]
	v_add_u32_e32 v160, v135, v136
	s_cbranch_vccz .LBB0_935
	s_cmp_gt_u32 s97, 1
	s_cselect_b64 vcc, -1, 0
	s_cmp_lt_u32 s97, 2
	s_cbranch_scc0 .LBB0_936
